# attention loop: wave priority dropped to 0 for the VALU-only softmax stretch between the QK and PV MFMA runs (raised again at the first PV MFMA)
# speedup vs baseline: 1.0239x; 1.0239x over previous
; DI void flash_item64(const u16* Qbase  , int ntb, int ntw, const u16* Kbase, const u16* Vtbase,
;                      u16* Obase  , char* smem) {
;     ...
; #pragma unroll
;     for (int qh = 0; qh < 2; qh++) {
;       float mx = -1e30f;
; #pragma unroll
;       for (int sub = 0; sub < 2; sub++)
; #pragma unroll
;         for (int i = 0; i < 16; i++) mx = fmaxf(mx, s[sub][qh][i]);
;       mx = xhalf_max(mx);
;       if (__any(mx > 8.f)) {
;         const float d = fmaxf(mx, 0.f);
;         const float alpha = __builtin_amdgcn_exp2f(-d);
;         mrun[qh] += d;
;         lrun[qh] *= alpha;
; #pragma unroll
;         for (int et = 0; et < 2; et++)
; #pragma unroll
;           for (int i = 0; i < 16; i++) o[qh][et][i] *= alpha;
; #pragma unroll
;         for (int sub = 0; sub < 2; sub++)
; #pragma unroll
;           for (int i = 0; i < 16; i++) s[sub][qh][i] -= d;
;       }
.Lqk_join_1:
	s_setprio 0
	v_mov_b32_e32 v236, v235
	s_nop 1
	v_permlane32_swap_b32_e32 v235, v236
	v_max_f32_e32 v236, v236, v236
	v_max_f32_e32 v235, v235, v235
	v_max_f32_e32 v235, v235, v236
	v_cmp_lt_f32_e32 vcc, s58, v235
	s_cbranch_vccz .LBB0_851
	v_max_f32_e32 v235, v235, v235
	v_max_f32_e32 v236, 0, v235
	v_exp_f32_e64 v238, -v236
	v_add_f32_e32 v234, v234, v236
	v_pk_add_f32 v[116:117], v[116:117], v[236:237] op_sel_hi:[1,0] neg_lo:[0,1] neg_hi:[0,1]
	v_pk_add_f32 v[118:119], v[118:119], v[236:237] op_sel_hi:[1,0] neg_lo:[0,1] neg_hi:[0,1]
	v_mul_f32_e32 v1, v1, v238
	v_pk_mul_f32 v[66:67], v[66:67], v[238:239] op_sel_hi:[1,0]
	v_pk_mul_f32 v[64:65], v[64:65], v[238:239] op_sel_hi:[1,0]
	v_pk_mul_f32 v[62:63], v[62:63], v[238:239] op_sel_hi:[1,0]
	v_pk_mul_f32 v[60:61], v[60:61], v[238:239] op_sel_hi:[1,0]
	v_pk_mul_f32 v[58:59], v[58:59], v[238:239] op_sel_hi:[1,0]
	v_pk_mul_f32 v[56:57], v[56:57], v[238:239] op_sel_hi:[1,0]
	v_pk_mul_f32 v[54:55], v[54:55], v[238:239] op_sel_hi:[1,0]
	v_pk_mul_f32 v[52:53], v[52:53], v[238:239] op_sel_hi:[1,0]
	v_pk_mul_f32 v[50:51], v[50:51], v[238:239] op_sel_hi:[1,0]
	v_pk_mul_f32 v[48:49], v[48:49], v[238:239] op_sel_hi:[1,0]
	v_pk_mul_f32 v[46:47], v[46:47], v[238:239] op_sel_hi:[1,0]
	v_pk_mul_f32 v[44:45], v[44:45], v[238:239] op_sel_hi:[1,0]
	v_pk_mul_f32 v[42:43], v[42:43], v[238:239] op_sel_hi:[1,0]
	v_pk_mul_f32 v[40:41], v[40:41], v[238:239] op_sel_hi:[1,0]
	v_pk_mul_f32 v[38:39], v[38:39], v[238:239] op_sel_hi:[1,0]
	v_pk_mul_f32 v[36:37], v[36:37], v[238:239] op_sel_hi:[1,0]
	v_pk_add_f32 v[120:121], v[120:121], v[236:237] op_sel_hi:[1,0] neg_lo:[0,1] neg_hi:[0,1]
	v_pk_add_f32 v[122:123], v[122:123], v[236:237] op_sel_hi:[1,0] neg_lo:[0,1] neg_hi:[0,1]
	v_pk_add_f32 v[124:125], v[124:125], v[236:237] op_sel_hi:[1,0] neg_lo:[0,1] neg_hi:[0,1]
	v_pk_add_f32 v[126:127], v[126:127], v[236:237] op_sel_hi:[1,0] neg_lo:[0,1] neg_hi:[0,1]
	v_pk_add_f32 v[128:129], v[128:129], v[236:237] op_sel_hi:[1,0] neg_lo:[0,1] neg_hi:[0,1]
	v_pk_add_f32 v[130:131], v[130:131], v[236:237] op_sel_hi:[1,0] neg_lo:[0,1] neg_hi:[0,1]
	v_pk_add_f32 v[84:85], v[84:85], v[236:237] op_sel_hi:[1,0] neg_lo:[0,1] neg_hi:[0,1]
	v_pk_add_f32 v[86:87], v[86:87], v[236:237] op_sel_hi:[1,0] neg_lo:[0,1] neg_hi:[0,1]
	v_pk_add_f32 v[88:89], v[88:89], v[236:237] op_sel_hi:[1,0] neg_lo:[0,1] neg_hi:[0,1]
	v_pk_add_f32 v[90:91], v[90:91], v[236:237] op_sel_hi:[1,0] neg_lo:[0,1] neg_hi:[0,1]
	v_pk_add_f32 v[92:93], v[92:93], v[236:237] op_sel_hi:[1,0] neg_lo:[0,1] neg_hi:[0,1]
	v_pk_add_f32 v[94:95], v[94:95], v[236:237] op_sel_hi:[1,0] neg_lo:[0,1] neg_hi:[0,1]
	v_pk_add_f32 v[96:97], v[96:97], v[236:237] op_sel_hi:[1,0] neg_lo:[0,1] neg_hi:[0,1]
	v_pk_add_f32 v[98:99], v[98:99], v[236:237] op_sel_hi:[1,0] neg_lo:[0,1] neg_hi:[0,1]

; #define MFMA(a, b, c) __builtin_amdgcn_mfma_f32_32x32x16_bf16((a), (b), (c), 0, 0, 0)
; DI unsigned pk2(float a, float b) { fv2 v = {a, b}; bfv2 r = __builtin_convertvector(v, bfv2); return __builtin_bit_cast(unsigned, r); }
; DI void flash_item64(const u16* Qbase  , int ntb, int ntw, const u16* Kbase, const u16* Vtbase,
;                      u16* Obase  , char* smem) {
;     ...
;       float psum = 0.f;
; #pragma unroll
;       for (int sub = 0; sub < 2; sub++)
; #pragma unroll
;         for (int i = 0; i < 16; i++) { float pv = __builtin_amdgcn_exp2f(s[sub][qh][i]); s[sub][qh][i] = pv; psum += pv; }
;       lrun[qh] += psum;
;     }
; #pragma unroll
;     for (int sub = 0; sub < 2; sub++)
; #pragma unroll
;       for (int st = 0; st < 2; st++) {
;         bf16x8 pb[2];
; #pragma unroll
;         for (int qh = 0; qh < 2; qh++) {
;           uint4 pp;
;           pp.x = pk2(s[sub][qh][8 * st + 0], s[sub][qh][8 * st + 1]); pp.y = pk2(s[sub][qh][8 * st + 2], s[sub][qh][8 * st + 3]);
;           pp.z = pk2(s[sub][qh][8 * st + 4], s[sub][qh][8 * st + 5]); pp.w = pk2(s[sub][qh][8 * st + 6], s[sub][qh][8 * st + 7]);
;           pb[qh] = __builtin_bit_cast(bf16x8, pp);
;         }
; #pragma unroll
;         for (int et = 0; et < 2; et++) {
;           bf16x8 a = *(const bf16x8*)(cV + et * 32 * LDV + sub * 32 + st * 16);
;           o[0][et] = MFMA(a, pb[0], o[0][et]);
;           o[1][et] = MFMA(a, pb[1], o[1][et]);
;         }
;       }
.LBB0_853:
	v_exp_f32_e32 v116, v116
	v_exp_f32_e32 v117, v117
	v_exp_f32_e32 v118, v118
	v_exp_f32_e32 v119, v119
	v_add_f32_e32 v235, 0, v116
	v_exp_f32_e32 v120, v120
	v_add_f32_e32 v235, v117, v235
	v_exp_f32_e32 v121, v121
	v_add_f32_e32 v235, v118, v235
	v_exp_f32_e32 v122, v122
	v_add_f32_e32 v235, v119, v235
	v_exp_f32_e32 v123, v123
	v_add_f32_e32 v235, v120, v235
	v_exp_f32_e32 v124, v124
	v_add_f32_e32 v235, v121, v235
	v_exp_f32_e32 v125, v125
	v_add_f32_e32 v235, v122, v235
	v_exp_f32_e32 v126, v126
	v_add_f32_e32 v235, v123, v235
	v_exp_f32_e32 v127, v127
	v_add_f32_e32 v235, v124, v235
	v_exp_f32_e32 v128, v128
	v_add_f32_e32 v235, v125, v235
	v_exp_f32_e32 v129, v129
	v_add_f32_e32 v235, v126, v235
	v_exp_f32_e32 v130, v130
	v_add_f32_e32 v235, v127, v235
	v_exp_f32_e32 v131, v131
	v_add_f32_e32 v235, v128, v235
	v_exp_f32_e32 v236, v84
	v_add_f32_e32 v84, v129, v235
	v_exp_f32_e32 v235, v85
	v_add_f32_e32 v84, v130, v84
	v_exp_f32_e32 v237, v86
	v_add_f32_e32 v84, v131, v84
	v_exp_f32_e32 v238, v87
	v_add_f32_e32 v84, v236, v84
	v_exp_f32_e32 v239, v88
	v_add_f32_e32 v84, v235, v84
	v_exp_f32_e32 v240, v89
	v_add_f32_e32 v84, v237, v84
	v_exp_f32_e32 v241, v90
	v_add_f32_e32 v84, v238, v84
	v_exp_f32_e32 v242, v91
	v_add_f32_e32 v84, v239, v84
	v_exp_f32_e32 v243, v92
	v_add_f32_e32 v84, v240, v84
	v_add_f32_e32 v84, v241, v84
	s_mulk_i32 s63, 0x2400
	v_add_f32_e32 v84, v242, v84
	v_add_u32_e32 v251, s63, v209
	v_add_f32_e32 v244, v243, v84
	ds_read_b128 v[84:87], v251 offset:26624
	v_exp_f32_e32 v253, v104
	v_exp_f32_e32 v254, v105
	v_cvt_pk_bf16_f32 v88, v116, v117
	v_exp_f32_e32 v116, v106
	v_exp_f32_e32 v117, v107
	ds_read_b128 v[104:107], v251 offset:31232
	v_exp_f32_e32 v248, v100
	v_exp_f32_e32 v249, v101
	v_exp_f32_e32 v250, v102
	v_exp_f32_e32 v252, v103
	v_exp_f32_e32 v245, v93
	v_exp_f32_e32 v246, v94
	v_exp_f32_e32 v247, v95
	v_cvt_pk_bf16_f32 v89, v118, v119
	v_cvt_pk_bf16_f32 v90, v120, v121
	v_cvt_pk_bf16_f32 v91, v122, v123
	ds_read_b128 v[92:95], v251 offset:26656
	v_cvt_pk_bf16_f32 v100, v248, v249
	v_cvt_pk_bf16_f32 v101, v250, v252
	v_cvt_pk_bf16_f32 v102, v253, v254
	v_cvt_pk_bf16_f32 v103, v116, v117
	s_waitcnt lgkmcnt(2)
	s_setprio 1
	v_mfma_f32_32x32x16_bf16 v[52:67], v[84:87], v[88:91], v[52:67]
	v_exp_f32_e32 v119, v96
	v_exp_f32_e32 v120, v97
	v_exp_f32_e32 v121, v98
	v_exp_f32_e32 v122, v99
	v_exp_f32_e32 v108, v108
	v_exp_f32_e32 v109, v109
	v_exp_f32_e32 v80, v80
	v_mfma_f32_32x32x16_bf16 v[20:35], v[84:87], v[100:103], v[20:35]
	v_add_f32_e32 v84, v245, v244
	v_add_f32_e32 v84, v246, v84
	v_add_f32_e32 v118, v247, v84
	ds_read_b128 v[84:87], v251 offset:31264
	v_cvt_pk_bf16_f32 v96, v108, v109
	v_exp_f32_e32 v81, v81
	v_exp_f32_e32 v82, v82
	s_waitcnt lgkmcnt(2)
	v_mfma_f32_32x32x16_bf16 v[36:51], v[104:107], v[88:91], v[36:51]
	v_add_f32_e32 v88, v119, v118
	v_add_f32_e32 v88, v120, v88
	v_add_f32_e32 v88, v121, v88
	v_add_f32_e32 v118, v122, v88
	v_cvt_pk_bf16_f32 v88, v124, v125
	v_cvt_pk_bf16_f32 v89, v126, v127
	v_cvt_pk_bf16_f32 v90, v128, v129
	v_mfma_f32_32x32x16_bf16 v[4:19], v[104:107], v[100:103], v[4:19]
	v_exp_f32_e32 v100, v110
	v_exp_f32_e32 v101, v111
	v_exp_f32_e32 v102, v112
	v_exp_f32_e32 v103, v113
	v_exp_f32_e32 v104, v114
	v_exp_f32_e32 v105, v115
	v_cvt_pk_bf16_f32 v91, v130, v131
	v_cvt_pk_bf16_f32 v97, v100, v101
	v_cvt_pk_bf16_f32 v98, v102, v103
	v_cvt_pk_bf16_f32 v99, v104, v105
	s_waitcnt lgkmcnt(1)
	v_mfma_f32_32x32x16_bf16 v[52:67], v[92:95], v[88:91], v[52:67]
	v_exp_f32_e32 v107, v68
	v_exp_f32_e32 v110, v69
	v_exp_f32_e32 v111, v70
	v_exp_f32_e32 v112, v71
	ds_read_b128 v[68:71], v251 offset:26688
	v_exp_f32_e32 v83, v83
	v_add_f32_e32 v1, v1, v118
	v_mfma_f32_32x32x16_bf16 v[20:35], v[92:95], v[96:99], v[20:35]
	v_add_f32_e32 v92, 0, v248
	v_add_f32_e32 v92, v249, v92
	v_add_f32_e32 v92, v250, v92
	v_add_f32_e32 v92, v252, v92
	v_add_f32_e32 v92, v253, v92
	v_add_f32_e32 v92, v254, v92
	s_waitcnt lgkmcnt(1)
	v_mfma_f32_32x32x16_bf16 v[4:19], v[84:87], v[96:99], v[4:19]
	v_exp_f32_e32 v96, v72
	v_exp_f32_e32 v97, v73
	v_exp_f32_e32 v98, v74
	v_exp_f32_e32 v99, v75
	v_cvt_pk_bf16_f32 v72, v107, v110
	v_cvt_pk_bf16_f32 v73, v111, v112
	v_cvt_pk_bf16_f32 v74, v96, v97
	v_mfma_f32_32x32x16_bf16 v[36:51], v[84:87], v[88:91], v[36:51]
	v_add_f32_e32 v88, v116, v92
	ds_read_b128 v[92:95], v251 offset:31296
	v_add_f32_e32 v106, v117, v88
	v_cvt_pk_bf16_f32 v84, v236, v235
	v_cvt_pk_bf16_f32 v85, v237, v238
	v_cvt_pk_bf16_f32 v86, v239, v240
	v_cvt_pk_bf16_f32 v87, v241, v242
	v_cvt_pk_bf16_f32 v75, v98, v99
	ds_read_b128 v[88:91], v251 offset:26720
	s_waitcnt lgkmcnt(2)
	v_mfma_f32_32x32x16_bf16 v[52:67], v[68:71], v[84:87], v[52:67]
	v_mfma_f32_32x32x16_bf16 v[20:35], v[68:71], v[72:75], v[20:35]
	v_add_f32_e32 v68, v108, v106
	v_add_f32_e32 v68, v109, v68
	v_add_f32_e32 v68, v100, v68
	v_add_f32_e32 v68, v101, v68
	v_add_f32_e32 v68, v102, v68
	v_add_f32_e32 v100, v103, v68
	ds_read_b128 v[68:71], v251 offset:31328
	s_waitcnt lgkmcnt(2)
	v_mfma_f32_32x32x16_bf16 v[36:51], v[92:95], v[84:87], v[36:51]
	v_add_f32_e32 v84, v104, v100
	v_add_f32_e32 v84, v105, v84
	v_add_f32_e32 v84, v107, v84
	v_add_f32_e32 v84, v110, v84
	v_add_f32_e32 v84, v111, v84
	v_add_f32_e32 v84, v112, v84
	v_exp_f32_e32 v85, v76
	v_mfma_f32_32x32x16_bf16 v[4:19], v[92:95], v[72:75], v[4:19]
	v_exp_f32_e32 v86, v77
	v_exp_f32_e32 v87, v78
	v_exp_f32_e32 v92, v79
	v_add_f32_e32 v84, v96, v84
	v_add_f32_e32 v84, v97, v84
	v_add_f32_e32 v84, v98, v84
	v_add_f32_e32 v84, v99, v84
	v_cvt_pk_bf16_f32 v72, v243, v245
	v_cvt_pk_bf16_f32 v73, v246, v247
	v_cvt_pk_bf16_f32 v74, v119, v120
	v_cvt_pk_bf16_f32 v75, v121, v122
	v_cvt_pk_bf16_f32 v76, v85, v86
	v_cvt_pk_bf16_f32 v77, v87, v92
	v_cvt_pk_bf16_f32 v78, v80, v81
	v_cvt_pk_bf16_f32 v79, v82, v83
	v_add_f32_e32 v84, v85, v84
	s_waitcnt lgkmcnt(1)
	v_mfma_f32_32x32x16_bf16 v[52:67], v[88:91], v[72:75], v[52:67]
	v_add_f32_e32 v84, v86, v84
	v_mfma_f32_32x32x16_bf16 v[20:35], v[88:91], v[76:79], v[20:35]
	s_waitcnt lgkmcnt(0)
	v_mfma_f32_32x32x16_bf16 v[36:51], v[68:71], v[72:75], v[36:51]
	v_add_f32_e32 v72, v87, v84
	v_add_f32_e32 v72, v92, v72
	v_add_f32_e32 v72, v80, v72
	v_add_f32_e32 v72, v81, v72
	v_add_f32_e32 v72, v82, v72
	v_add_f32_e32 v72, v83, v72
	v_add_f32_e32 v202, v202, v72
	v_mfma_f32_32x32x16_bf16 v[4:19], v[68:71], v[76:79], v[4:19]
	s_setprio 0

; DI void flash_item64(const u16* Qbase  , int ntb, int ntw, const u16* Kbase, const u16* Vtbase,
;                      u16* Obase  , char* smem) {
;     ...
; #pragma unroll
;     for (int qh = 0; qh < 2; qh++) {
;       float mx = -1e30f;
; #pragma unroll
;       for (int sub = 0; sub < 2; sub++)
; #pragma unroll
;         for (int i = 0; i < 16; i++) mx = fmaxf(mx, s[sub][qh][i]);
;       mx = xhalf_max(mx);
;       if (__any(mx > 8.f)) {
;         const float d = fmaxf(mx, 0.f);
;         const float alpha = __builtin_amdgcn_exp2f(-d);
;         mrun[qh] += d;
;         lrun[qh] *= alpha;
; #pragma unroll
;         for (int et = 0; et < 2; et++)
; #pragma unroll
;           for (int i = 0; i < 16; i++) o[qh][et][i] *= alpha;
; #pragma unroll
;         for (int sub = 0; sub < 2; sub++)
; #pragma unroll
;           for (int i = 0; i < 16; i++) s[sub][qh][i] -= d;
;       }
.Lqk_join_2:
	s_setprio 0
	v_mov_b32_e32 v236, v235
	s_nop 1
	v_permlane32_swap_b32_e32 v235, v236
	v_max_f32_e32 v236, v236, v236
	v_max_f32_e32 v235, v235, v235
	v_max_f32_e32 v235, v235, v236
	v_cmp_lt_f32_e32 vcc, s50, v235
	s_cbranch_vccz .LBB0_2253
	v_max_f32_e32 v235, v235, v235
	v_max_f32_e32 v236, 0, v235
	v_exp_f32_e64 v238, -v236
	v_add_f32_e32 v234, v234, v236
	v_pk_add_f32 v[116:117], v[116:117], v[236:237] op_sel_hi:[1,0] neg_lo:[0,1] neg_hi:[0,1]
	v_pk_add_f32 v[118:119], v[118:119], v[236:237] op_sel_hi:[1,0] neg_lo:[0,1] neg_hi:[0,1]
	v_mul_f32_e32 v1, v1, v238
	v_pk_mul_f32 v[66:67], v[66:67], v[238:239] op_sel_hi:[1,0]
	v_pk_mul_f32 v[64:65], v[64:65], v[238:239] op_sel_hi:[1,0]
	v_pk_mul_f32 v[62:63], v[62:63], v[238:239] op_sel_hi:[1,0]
	v_pk_mul_f32 v[60:61], v[60:61], v[238:239] op_sel_hi:[1,0]
	v_pk_mul_f32 v[58:59], v[58:59], v[238:239] op_sel_hi:[1,0]
	v_pk_mul_f32 v[56:57], v[56:57], v[238:239] op_sel_hi:[1,0]
	v_pk_mul_f32 v[54:55], v[54:55], v[238:239] op_sel_hi:[1,0]
	v_pk_mul_f32 v[52:53], v[52:53], v[238:239] op_sel_hi:[1,0]
	v_pk_mul_f32 v[50:51], v[50:51], v[238:239] op_sel_hi:[1,0]
	v_pk_mul_f32 v[48:49], v[48:49], v[238:239] op_sel_hi:[1,0]
	v_pk_mul_f32 v[46:47], v[46:47], v[238:239] op_sel_hi:[1,0]
	v_pk_mul_f32 v[44:45], v[44:45], v[238:239] op_sel_hi:[1,0]
	v_pk_mul_f32 v[42:43], v[42:43], v[238:239] op_sel_hi:[1,0]
	v_pk_mul_f32 v[40:41], v[40:41], v[238:239] op_sel_hi:[1,0]
	v_pk_mul_f32 v[38:39], v[38:39], v[238:239] op_sel_hi:[1,0]
	v_pk_mul_f32 v[36:37], v[36:37], v[238:239] op_sel_hi:[1,0]
	v_pk_add_f32 v[120:121], v[120:121], v[236:237] op_sel_hi:[1,0] neg_lo:[0,1] neg_hi:[0,1]
	v_pk_add_f32 v[122:123], v[122:123], v[236:237] op_sel_hi:[1,0] neg_lo:[0,1] neg_hi:[0,1]
	v_pk_add_f32 v[124:125], v[124:125], v[236:237] op_sel_hi:[1,0] neg_lo:[0,1] neg_hi:[0,1]
	v_pk_add_f32 v[126:127], v[126:127], v[236:237] op_sel_hi:[1,0] neg_lo:[0,1] neg_hi:[0,1]
	v_pk_add_f32 v[128:129], v[128:129], v[236:237] op_sel_hi:[1,0] neg_lo:[0,1] neg_hi:[0,1]
	v_pk_add_f32 v[130:131], v[130:131], v[236:237] op_sel_hi:[1,0] neg_lo:[0,1] neg_hi:[0,1]
	v_pk_add_f32 v[84:85], v[84:85], v[236:237] op_sel_hi:[1,0] neg_lo:[0,1] neg_hi:[0,1]
	v_pk_add_f32 v[86:87], v[86:87], v[236:237] op_sel_hi:[1,0] neg_lo:[0,1] neg_hi:[0,1]
	v_pk_add_f32 v[88:89], v[88:89], v[236:237] op_sel_hi:[1,0] neg_lo:[0,1] neg_hi:[0,1]
	v_pk_add_f32 v[90:91], v[90:91], v[236:237] op_sel_hi:[1,0] neg_lo:[0,1] neg_hi:[0,1]
	v_pk_add_f32 v[92:93], v[92:93], v[236:237] op_sel_hi:[1,0] neg_lo:[0,1] neg_hi:[0,1]
	v_pk_add_f32 v[94:95], v[94:95], v[236:237] op_sel_hi:[1,0] neg_lo:[0,1] neg_hi:[0,1]
	v_pk_add_f32 v[96:97], v[96:97], v[236:237] op_sel_hi:[1,0] neg_lo:[0,1] neg_hi:[0,1]
	v_pk_add_f32 v[98:99], v[98:99], v[236:237] op_sel_hi:[1,0] neg_lo:[0,1] neg_hi:[0,1]

; #define MFMA(a, b, c) __builtin_amdgcn_mfma_f32_32x32x16_bf16((a), (b), (c), 0, 0, 0)
; DI unsigned pk2(float a, float b) { fv2 v = {a, b}; bfv2 r = __builtin_convertvector(v, bfv2); return __builtin_bit_cast(unsigned, r); }
; DI void flash_item64(const u16* Qbase  , int ntb, int ntw, const u16* Kbase, const u16* Vtbase,
;                      u16* Obase  , char* smem) {
;     ...
;       float psum = 0.f;
; #pragma unroll
;       for (int sub = 0; sub < 2; sub++)
; #pragma unroll
;         for (int i = 0; i < 16; i++) { float pv = __builtin_amdgcn_exp2f(s[sub][qh][i]); s[sub][qh][i] = pv; psum += pv; }
;       lrun[qh] += psum;
;     }
; #pragma unroll
;     for (int sub = 0; sub < 2; sub++)
; #pragma unroll
;       for (int st = 0; st < 2; st++) {
;         bf16x8 pb[2];
; #pragma unroll
;         for (int qh = 0; qh < 2; qh++) {
;           uint4 pp;
;           pp.x = pk2(s[sub][qh][8 * st + 0], s[sub][qh][8 * st + 1]); pp.y = pk2(s[sub][qh][8 * st + 2], s[sub][qh][8 * st + 3]);
;           pp.z = pk2(s[sub][qh][8 * st + 4], s[sub][qh][8 * st + 5]); pp.w = pk2(s[sub][qh][8 * st + 6], s[sub][qh][8 * st + 7]);
;           pb[qh] = __builtin_bit_cast(bf16x8, pp);
;         }
; #pragma unroll
;         for (int et = 0; et < 2; et++) {
;           bf16x8 a = *(const bf16x8*)(cV + et * 32 * LDV + sub * 32 + st * 16);
;           o[0][et] = MFMA(a, pb[0], o[0][et]);
;           o[1][et] = MFMA(a, pb[1], o[1][et]);
;         }
;       }
.LBB0_2255:
	v_exp_f32_e32 v116, v116
	v_exp_f32_e32 v117, v117
	v_exp_f32_e32 v118, v118
	v_exp_f32_e32 v119, v119
	v_add_f32_e32 v235, 0, v116
	v_exp_f32_e32 v120, v120
	v_add_f32_e32 v235, v117, v235
	v_exp_f32_e32 v121, v121
	v_add_f32_e32 v235, v118, v235
	v_exp_f32_e32 v122, v122
	v_add_f32_e32 v235, v119, v235
	v_exp_f32_e32 v123, v123
	v_add_f32_e32 v235, v120, v235
	v_exp_f32_e32 v124, v124
	v_add_f32_e32 v235, v121, v235
	v_exp_f32_e32 v125, v125
	v_add_f32_e32 v235, v122, v235
	v_exp_f32_e32 v126, v126
	v_add_f32_e32 v235, v123, v235
	v_exp_f32_e32 v127, v127
	v_add_f32_e32 v235, v124, v235
	v_exp_f32_e32 v128, v128
	v_add_f32_e32 v235, v125, v235
	v_exp_f32_e32 v129, v129
	v_add_f32_e32 v235, v126, v235
	v_exp_f32_e32 v130, v130
	v_add_f32_e32 v235, v127, v235
	v_exp_f32_e32 v131, v131
	v_add_f32_e32 v235, v128, v235
	v_exp_f32_e32 v236, v84
	v_add_f32_e32 v84, v129, v235
	v_exp_f32_e32 v235, v85
	v_add_f32_e32 v84, v130, v84
	v_exp_f32_e32 v237, v86
	v_add_f32_e32 v84, v131, v84
	v_exp_f32_e32 v238, v87
	v_add_f32_e32 v84, v236, v84
	v_exp_f32_e32 v239, v88
	v_add_f32_e32 v84, v235, v84
	v_exp_f32_e32 v240, v89
	v_add_f32_e32 v84, v237, v84
	v_exp_f32_e32 v241, v90
	v_add_f32_e32 v84, v238, v84
	v_exp_f32_e32 v242, v91
	v_add_f32_e32 v84, v239, v84
	v_exp_f32_e32 v243, v92
	v_add_f32_e32 v84, v240, v84
	v_add_f32_e32 v84, v241, v84
	s_mulk_i32 s61, 0x2400
	v_add_f32_e32 v84, v242, v84
	v_add_u32_e32 v251, s61, v209
	v_add_f32_e32 v244, v243, v84
	ds_read_b128 v[84:87], v251 offset:26624
	v_exp_f32_e32 v253, v104
	v_exp_f32_e32 v254, v105
	v_cvt_pk_bf16_f32 v88, v116, v117
	v_exp_f32_e32 v116, v106
	v_exp_f32_e32 v117, v107
	ds_read_b128 v[104:107], v251 offset:31232
	v_exp_f32_e32 v248, v100
	v_exp_f32_e32 v249, v101
	v_exp_f32_e32 v250, v102
	v_exp_f32_e32 v252, v103
	v_exp_f32_e32 v245, v93
	v_exp_f32_e32 v246, v94
	v_exp_f32_e32 v247, v95
	v_cvt_pk_bf16_f32 v89, v118, v119
	v_cvt_pk_bf16_f32 v90, v120, v121
	v_cvt_pk_bf16_f32 v91, v122, v123
	ds_read_b128 v[92:95], v251 offset:26656
	v_cvt_pk_bf16_f32 v100, v248, v249
	v_cvt_pk_bf16_f32 v101, v250, v252
	v_cvt_pk_bf16_f32 v102, v253, v254
	v_cvt_pk_bf16_f32 v103, v116, v117
	s_waitcnt lgkmcnt(2)
	s_setprio 1
	v_mfma_f32_32x32x16_bf16 v[52:67], v[84:87], v[88:91], v[52:67]
	v_exp_f32_e32 v119, v96
	v_exp_f32_e32 v120, v97
	v_exp_f32_e32 v121, v98
	v_exp_f32_e32 v122, v99
	v_exp_f32_e32 v108, v108
	v_exp_f32_e32 v109, v109
	v_exp_f32_e32 v80, v80
	v_mfma_f32_32x32x16_bf16 v[20:35], v[84:87], v[100:103], v[20:35]
	v_add_f32_e32 v84, v245, v244
	v_add_f32_e32 v84, v246, v84
	v_add_f32_e32 v118, v247, v84
	ds_read_b128 v[84:87], v251 offset:31264
	v_cvt_pk_bf16_f32 v96, v108, v109
	v_exp_f32_e32 v81, v81
	v_exp_f32_e32 v82, v82
	s_waitcnt lgkmcnt(2)
	v_mfma_f32_32x32x16_bf16 v[36:51], v[104:107], v[88:91], v[36:51]
	v_add_f32_e32 v88, v119, v118
	v_add_f32_e32 v88, v120, v88
	v_add_f32_e32 v88, v121, v88
	v_add_f32_e32 v118, v122, v88
	v_cvt_pk_bf16_f32 v88, v124, v125
	v_cvt_pk_bf16_f32 v89, v126, v127
	v_cvt_pk_bf16_f32 v90, v128, v129
	v_mfma_f32_32x32x16_bf16 v[4:19], v[104:107], v[100:103], v[4:19]
	v_exp_f32_e32 v100, v110
	v_exp_f32_e32 v101, v111
	v_exp_f32_e32 v102, v112
	v_exp_f32_e32 v103, v113
	v_exp_f32_e32 v104, v114
	v_exp_f32_e32 v105, v115
	v_cvt_pk_bf16_f32 v91, v130, v131
	v_cvt_pk_bf16_f32 v97, v100, v101
	v_cvt_pk_bf16_f32 v98, v102, v103
	v_cvt_pk_bf16_f32 v99, v104, v105
	s_waitcnt lgkmcnt(1)
	v_mfma_f32_32x32x16_bf16 v[52:67], v[92:95], v[88:91], v[52:67]
	v_exp_f32_e32 v107, v68
	v_exp_f32_e32 v110, v69
	v_exp_f32_e32 v111, v70
	v_exp_f32_e32 v112, v71
	ds_read_b128 v[68:71], v251 offset:26688
	v_exp_f32_e32 v83, v83
	v_add_f32_e32 v1, v1, v118
	v_mfma_f32_32x32x16_bf16 v[20:35], v[92:95], v[96:99], v[20:35]
	v_add_f32_e32 v92, 0, v248
	v_add_f32_e32 v92, v249, v92
	v_add_f32_e32 v92, v250, v92
	v_add_f32_e32 v92, v252, v92
	v_add_f32_e32 v92, v253, v92
	v_add_f32_e32 v92, v254, v92
	s_waitcnt lgkmcnt(1)
	v_mfma_f32_32x32x16_bf16 v[4:19], v[84:87], v[96:99], v[4:19]
	v_exp_f32_e32 v96, v72
	v_exp_f32_e32 v97, v73
	v_exp_f32_e32 v98, v74
	v_exp_f32_e32 v99, v75
	v_cvt_pk_bf16_f32 v72, v107, v110
	v_cvt_pk_bf16_f32 v73, v111, v112
	v_cvt_pk_bf16_f32 v74, v96, v97
	v_mfma_f32_32x32x16_bf16 v[36:51], v[84:87], v[88:91], v[36:51]
	v_add_f32_e32 v88, v116, v92
	ds_read_b128 v[92:95], v251 offset:31296
	v_add_f32_e32 v106, v117, v88
	v_cvt_pk_bf16_f32 v84, v236, v235
	v_cvt_pk_bf16_f32 v85, v237, v238
	v_cvt_pk_bf16_f32 v86, v239, v240
	v_cvt_pk_bf16_f32 v87, v241, v242
	v_cvt_pk_bf16_f32 v75, v98, v99
	ds_read_b128 v[88:91], v251 offset:26720
	s_waitcnt lgkmcnt(2)
	v_mfma_f32_32x32x16_bf16 v[52:67], v[68:71], v[84:87], v[52:67]
	v_mfma_f32_32x32x16_bf16 v[20:35], v[68:71], v[72:75], v[20:35]
	v_add_f32_e32 v68, v108, v106
	v_add_f32_e32 v68, v109, v68
	v_add_f32_e32 v68, v100, v68
	v_add_f32_e32 v68, v101, v68
	v_add_f32_e32 v68, v102, v68
	v_add_f32_e32 v100, v103, v68
	ds_read_b128 v[68:71], v251 offset:31328
	s_waitcnt lgkmcnt(2)
	v_mfma_f32_32x32x16_bf16 v[36:51], v[92:95], v[84:87], v[36:51]
	v_add_f32_e32 v84, v104, v100
	v_add_f32_e32 v84, v105, v84
	v_add_f32_e32 v84, v107, v84
	v_add_f32_e32 v84, v110, v84
	v_add_f32_e32 v84, v111, v84
	v_add_f32_e32 v84, v112, v84
	v_exp_f32_e32 v85, v76
	v_mfma_f32_32x32x16_bf16 v[4:19], v[92:95], v[72:75], v[4:19]
	v_exp_f32_e32 v86, v77
	v_exp_f32_e32 v87, v78
	v_exp_f32_e32 v92, v79
	v_add_f32_e32 v84, v96, v84
	v_add_f32_e32 v84, v97, v84
	v_add_f32_e32 v84, v98, v84
	v_add_f32_e32 v84, v99, v84
	v_cvt_pk_bf16_f32 v72, v243, v245
	v_cvt_pk_bf16_f32 v73, v246, v247
	v_cvt_pk_bf16_f32 v74, v119, v120
	v_cvt_pk_bf16_f32 v75, v121, v122
	v_cvt_pk_bf16_f32 v76, v85, v86
	v_cvt_pk_bf16_f32 v77, v87, v92
	v_cvt_pk_bf16_f32 v78, v80, v81
	v_cvt_pk_bf16_f32 v79, v82, v83
	v_add_f32_e32 v84, v85, v84
	s_waitcnt lgkmcnt(1)
	v_mfma_f32_32x32x16_bf16 v[52:67], v[88:91], v[72:75], v[52:67]
	v_add_f32_e32 v84, v86, v84
	v_mfma_f32_32x32x16_bf16 v[20:35], v[88:91], v[76:79], v[20:35]
	s_waitcnt lgkmcnt(0)
	v_mfma_f32_32x32x16_bf16 v[36:51], v[68:71], v[72:75], v[36:51]
	v_add_f32_e32 v72, v87, v84
	v_add_f32_e32 v72, v92, v72
	v_add_f32_e32 v72, v80, v72
	v_add_f32_e32 v72, v81, v72
	v_add_f32_e32 v72, v82, v72
	v_add_f32_e32 v72, v83, v72
	v_add_f32_e32 v202, v202, v72
	v_mfma_f32_32x32x16_bf16 v[4:19], v[68:71], v[76:79], v[4:19]
	s_setprio 0
